# idle blocks of the last (partial) GEMM round convert upcoming bf16 weights; inter-layer convert phase removed, initial convert shortened
# speedup vs baseline: 1.0536x; 1.0165x over previous
.LBB0_250:
	s_cmp_lt_u32 s2, 85
	s_cbranch_scc1 .Lic2_no
	v_writelane_b32 v253, s0, 0
	v_writelane_b32 v253, s1, 1
	v_writelane_b32 v253, s2, 2
	v_writelane_b32 v253, s3, 3
	v_writelane_b32 v253, s4, 4
	v_writelane_b32 v253, s5, 5
	v_writelane_b32 v253, s6, 6
	v_writelane_b32 v253, s7, 7
	v_writelane_b32 v253, s8, 8
	v_writelane_b32 v253, s9, 9
	v_writelane_b32 v253, s10, 10
	v_writelane_b32 v253, s11, 11
	v_writelane_b32 v253, s12, 12
	v_writelane_b32 v253, s13, 13
	v_writelane_b32 v253, s14, 14
	v_writelane_b32 v253, s15, 15
	v_writelane_b32 v253, s16, 16
	v_writelane_b32 v253, s17, 17
	v_writelane_b32 v253, s18, 18
	v_writelane_b32 v253, s19, 19
	v_writelane_b32 v253, s20, 20
	v_writelane_b32 v253, s21, 21
	v_writelane_b32 v253, s22, 22
	v_writelane_b32 v253, s23, 23
	v_writelane_b32 v253, s24, 24
	v_writelane_b32 v253, s25, 25
	v_writelane_b32 v253, s26, 26
	v_writelane_b32 v253, s27, 27
	v_writelane_b32 v253, s28, 28
	v_writelane_b32 v253, s29, 29
	v_writelane_b32 v253, s30, 30
	v_writelane_b32 v253, s31, 31
	v_writelane_b32 v253, s32, 32
	v_writelane_b32 v253, s33, 33
	v_writelane_b32 v253, s34, 34
	v_writelane_b32 v253, s35, 35
	v_writelane_b32 v253, s36, 36
	v_writelane_b32 v253, s37, 37
	v_writelane_b32 v253, s38, 38
	v_writelane_b32 v253, s39, 39
	v_writelane_b32 v253, s40, 40
	v_writelane_b32 v253, s41, 41
	v_writelane_b32 v253, s42, 42
	v_writelane_b32 v253, s43, 43
	v_writelane_b32 v253, s44, 44
	v_writelane_b32 v253, s45, 45
	v_writelane_b32 v253, s46, 46
	v_writelane_b32 v253, s47, 47
	v_writelane_b32 v253, s48, 48
	v_writelane_b32 v253, s49, 49
	v_writelane_b32 v253, s50, 50
	v_writelane_b32 v253, s51, 51
	v_writelane_b32 v253, s52, 52
	v_writelane_b32 v253, s53, 53
	v_writelane_b32 v253, s54, 54
	v_writelane_b32 v253, s55, 55
	v_writelane_b32 v253, s56, 56
	v_writelane_b32 v253, s57, 57
	v_writelane_b32 v253, s58, 58
	v_writelane_b32 v253, s59, 59
	v_writelane_b32 v253, s60, 60
	v_writelane_b32 v253, s61, 61
	v_writelane_b32 v253, s62, 62
	v_writelane_b32 v253, s63, 63
	v_writelane_b32 v254, s64, 0
	v_writelane_b32 v254, s65, 1
	v_writelane_b32 v254, s66, 2
	v_writelane_b32 v254, s67, 3
	v_writelane_b32 v254, s68, 4
	v_writelane_b32 v254, s69, 5
	v_writelane_b32 v254, s70, 6
	v_writelane_b32 v254, s71, 7
	v_writelane_b32 v254, s72, 8
	v_writelane_b32 v254, s73, 9
	v_writelane_b32 v254, s74, 10
	v_writelane_b32 v254, s75, 11
	v_writelane_b32 v254, s76, 12
	v_writelane_b32 v254, s77, 13
	v_writelane_b32 v254, s78, 14
	v_writelane_b32 v254, s79, 15
	v_writelane_b32 v254, s80, 16
	v_writelane_b32 v254, s81, 17
	v_writelane_b32 v254, s82, 18
	v_writelane_b32 v254, s83, 19
	v_writelane_b32 v254, s84, 20
	v_writelane_b32 v254, s85, 21
	v_writelane_b32 v254, s86, 22
	v_writelane_b32 v254, s87, 23
	v_writelane_b32 v254, s88, 24
	v_writelane_b32 v254, s89, 25
	v_writelane_b32 v254, s90, 26
	v_writelane_b32 v254, s91, 27
	v_writelane_b32 v254, s92, 28
	v_writelane_b32 v254, s93, 29
	v_writelane_b32 v254, s94, 30
	v_writelane_b32 v254, s95, 31
	v_writelane_b32 v254, s96, 32
	v_writelane_b32 v254, s97, 33
	v_writelane_b32 v254, s98, 34
	v_writelane_b32 v254, s99, 35
	v_readlane_b32 s0, v249, 62
	v_readlane_b32 s1, v248, 8
	s_cmp_eq_u32 s0, 1
	s_cbranch_scc0 .Lic2_c1
	s_mov_b32 s3, 0x0
	s_mov_b32 s101, 0x57f
	s_mov_b32 s52, 1
	s_branch .Lic2_go
.Lic2_c1:
	s_branch .Lconv_ret2
.Lic2_go:
	s_sub_i32 s0, s2, 85
	s_add_i32 s3, s3, s0
	s_sub_i32 s3, s3, 171
	v_writelane_b32 v255, s3, 0
	v_writelane_b32 v255, 2, 1
	s_movk_i32 s100, 171
	s_branch .Ltramp_call2
.Lconv_ret2:
	v_readlane_b32 s0, v253, 0
	v_readlane_b32 s1, v253, 1
	v_readlane_b32 s2, v253, 2
	v_readlane_b32 s3, v253, 3
	v_readlane_b32 s4, v253, 4
	v_readlane_b32 s5, v253, 5
	v_readlane_b32 s6, v253, 6
	v_readlane_b32 s7, v253, 7
	v_readlane_b32 s8, v253, 8
	v_readlane_b32 s9, v253, 9
	v_readlane_b32 s10, v253, 10
	v_readlane_b32 s11, v253, 11
	v_readlane_b32 s12, v253, 12
	v_readlane_b32 s13, v253, 13
	v_readlane_b32 s14, v253, 14
	v_readlane_b32 s15, v253, 15
	v_readlane_b32 s16, v253, 16
	v_readlane_b32 s17, v253, 17
	v_readlane_b32 s18, v253, 18
	v_readlane_b32 s19, v253, 19
	v_readlane_b32 s20, v253, 20
	v_readlane_b32 s21, v253, 21
	v_readlane_b32 s22, v253, 22
	v_readlane_b32 s23, v253, 23
	v_readlane_b32 s24, v253, 24
	v_readlane_b32 s25, v253, 25
	v_readlane_b32 s26, v253, 26
	v_readlane_b32 s27, v253, 27
	v_readlane_b32 s28, v253, 28
	v_readlane_b32 s29, v253, 29
	v_readlane_b32 s30, v253, 30
	v_readlane_b32 s31, v253, 31
	v_readlane_b32 s32, v253, 32
	v_readlane_b32 s33, v253, 33
	v_readlane_b32 s34, v253, 34
	v_readlane_b32 s35, v253, 35
	v_readlane_b32 s36, v253, 36
	v_readlane_b32 s37, v253, 37
	v_readlane_b32 s38, v253, 38
	v_readlane_b32 s39, v253, 39
	v_readlane_b32 s40, v253, 40
	v_readlane_b32 s41, v253, 41
	v_readlane_b32 s42, v253, 42
	v_readlane_b32 s43, v253, 43
	v_readlane_b32 s44, v253, 44
	v_readlane_b32 s45, v253, 45
	v_readlane_b32 s46, v253, 46
	v_readlane_b32 s47, v253, 47
	v_readlane_b32 s48, v253, 48
	v_readlane_b32 s49, v253, 49
	v_readlane_b32 s50, v253, 50
	v_readlane_b32 s51, v253, 51
	v_readlane_b32 s52, v253, 52
	v_readlane_b32 s53, v253, 53
	v_readlane_b32 s54, v253, 54
	v_readlane_b32 s55, v253, 55
	v_readlane_b32 s56, v253, 56
	v_readlane_b32 s57, v253, 57
	v_readlane_b32 s58, v253, 58
	v_readlane_b32 s59, v253, 59
	v_readlane_b32 s60, v253, 60
	v_readlane_b32 s61, v253, 61
	v_readlane_b32 s62, v253, 62
	v_readlane_b32 s63, v253, 63
	v_readlane_b32 s64, v254, 0
	v_readlane_b32 s65, v254, 1
	v_readlane_b32 s66, v254, 2
	v_readlane_b32 s67, v254, 3
	v_readlane_b32 s68, v254, 4
	v_readlane_b32 s69, v254, 5
	v_readlane_b32 s70, v254, 6
	v_readlane_b32 s71, v254, 7
	v_readlane_b32 s72, v254, 8
	v_readlane_b32 s73, v254, 9
	v_readlane_b32 s74, v254, 10
	v_readlane_b32 s75, v254, 11
	v_readlane_b32 s76, v254, 12
	v_readlane_b32 s77, v254, 13
	v_readlane_b32 s78, v254, 14
	v_readlane_b32 s79, v254, 15
	v_readlane_b32 s80, v254, 16
	v_readlane_b32 s81, v254, 17
	v_readlane_b32 s82, v254, 18
	v_readlane_b32 s83, v254, 19
	v_readlane_b32 s84, v254, 20
	v_readlane_b32 s85, v254, 21
	v_readlane_b32 s86, v254, 22
	v_readlane_b32 s87, v254, 23
	v_readlane_b32 s88, v254, 24
	v_readlane_b32 s89, v254, 25
	v_readlane_b32 s90, v254, 26
	v_readlane_b32 s91, v254, 27
	v_readlane_b32 s92, v254, 28
	v_readlane_b32 s93, v254, 29
	v_readlane_b32 s94, v254, 30
	v_readlane_b32 s95, v254, 31
	v_readlane_b32 s96, v254, 32
	v_readlane_b32 s97, v254, 33
	v_readlane_b32 s98, v254, 34
	v_readlane_b32 s99, v254, 35
	s_nop 4

.LBB0_1342:
	s_cmp_lt_u32 s2, 150
	s_cbranch_scc1 .Lic1_no
	v_writelane_b32 v253, s0, 0
	v_writelane_b32 v253, s1, 1
	v_writelane_b32 v253, s2, 2
	v_writelane_b32 v253, s3, 3
	v_writelane_b32 v253, s4, 4
	v_writelane_b32 v253, s5, 5
	v_writelane_b32 v253, s6, 6
	v_writelane_b32 v253, s7, 7
	v_writelane_b32 v253, s8, 8
	v_writelane_b32 v253, s9, 9
	v_writelane_b32 v253, s10, 10
	v_writelane_b32 v253, s11, 11
	v_writelane_b32 v253, s12, 12
	v_writelane_b32 v253, s13, 13
	v_writelane_b32 v253, s14, 14
	v_writelane_b32 v253, s15, 15
	v_writelane_b32 v253, s16, 16
	v_writelane_b32 v253, s17, 17
	v_writelane_b32 v253, s18, 18
	v_writelane_b32 v253, s19, 19
	v_writelane_b32 v253, s20, 20
	v_writelane_b32 v253, s21, 21
	v_writelane_b32 v253, s22, 22
	v_writelane_b32 v253, s23, 23
	v_writelane_b32 v253, s24, 24
	v_writelane_b32 v253, s25, 25
	v_writelane_b32 v253, s26, 26
	v_writelane_b32 v253, s27, 27
	v_writelane_b32 v253, s28, 28
	v_writelane_b32 v253, s29, 29
	v_writelane_b32 v253, s30, 30
	v_writelane_b32 v253, s31, 31
	v_writelane_b32 v253, s32, 32
	v_writelane_b32 v253, s33, 33
	v_writelane_b32 v253, s34, 34
	v_writelane_b32 v253, s35, 35
	v_writelane_b32 v253, s36, 36
	v_writelane_b32 v253, s37, 37
	v_writelane_b32 v253, s38, 38
	v_writelane_b32 v253, s39, 39
	v_writelane_b32 v253, s40, 40
	v_writelane_b32 v253, s41, 41
	v_writelane_b32 v253, s42, 42
	v_writelane_b32 v253, s43, 43
	v_writelane_b32 v253, s44, 44
	v_writelane_b32 v253, s45, 45
	v_writelane_b32 v253, s46, 46
	v_writelane_b32 v253, s47, 47
	v_writelane_b32 v253, s48, 48
	v_writelane_b32 v253, s49, 49
	v_writelane_b32 v253, s50, 50
	v_writelane_b32 v253, s51, 51
	v_writelane_b32 v253, s52, 52
	v_writelane_b32 v253, s53, 53
	v_writelane_b32 v253, s54, 54
	v_writelane_b32 v253, s55, 55
	v_writelane_b32 v253, s56, 56
	v_writelane_b32 v253, s57, 57
	v_writelane_b32 v253, s58, 58
	v_writelane_b32 v253, s59, 59
	v_writelane_b32 v253, s60, 60
	v_writelane_b32 v253, s61, 61
	v_writelane_b32 v253, s62, 62
	v_writelane_b32 v253, s63, 63
	v_writelane_b32 v254, s64, 0
	v_writelane_b32 v254, s65, 1
	v_writelane_b32 v254, s66, 2
	v_writelane_b32 v254, s67, 3
	v_writelane_b32 v254, s68, 4
	v_writelane_b32 v254, s69, 5
	v_writelane_b32 v254, s70, 6
	v_writelane_b32 v254, s71, 7
	v_writelane_b32 v254, s72, 8
	v_writelane_b32 v254, s73, 9
	v_writelane_b32 v254, s74, 10
	v_writelane_b32 v254, s75, 11
	v_writelane_b32 v254, s76, 12
	v_writelane_b32 v254, s77, 13
	v_writelane_b32 v254, s78, 14
	v_writelane_b32 v254, s79, 15
	v_writelane_b32 v254, s80, 16
	v_writelane_b32 v254, s81, 17
	v_writelane_b32 v254, s82, 18
	v_writelane_b32 v254, s83, 19
	v_writelane_b32 v254, s84, 20
	v_writelane_b32 v254, s85, 21
	v_writelane_b32 v254, s86, 22
	v_writelane_b32 v254, s87, 23
	v_writelane_b32 v254, s88, 24
	v_writelane_b32 v254, s89, 25
	v_writelane_b32 v254, s90, 26
	v_writelane_b32 v254, s91, 27
	v_writelane_b32 v254, s92, 28
	v_writelane_b32 v254, s93, 29
	v_writelane_b32 v254, s94, 30
	v_writelane_b32 v254, s95, 31
	v_writelane_b32 v254, s96, 32
	v_writelane_b32 v254, s97, 33
	v_writelane_b32 v254, s98, 34
	v_writelane_b32 v254, s99, 35
	v_readlane_b32 s0, v249, 62
	v_readlane_b32 s1, v248, 8
	s_cmp_eq_u32 s0, 1
	s_cbranch_scc0 .Lic1_c1
	s_cmp_eq_u32 s1, 0
	s_cbranch_scc1 .Lic1_c1
	s_mov_b32 s3, 0xfc0
	s_mov_b32 s101, 0x17bf
	s_mov_b32 s52, 0
	s_branch .Lic1_go
.Lic1_c1:
	s_cmp_eq_u32 s0, 1
	s_cbranch_scc0 .Lic1_c2
	s_cmp_eq_u32 s1, 0
	s_cbranch_scc0 .Lic1_c2
	s_mov_b32 s3, 0x580
	s_mov_b32 s101, 0xd7f
	s_mov_b32 s52, 1
	s_branch .Lic1_go
.Lic1_c2:
	s_cmp_eq_u32 s0, 2
	s_cbranch_scc0 .Lic1_c3
	s_cmp_eq_u32 s1, 0
	s_cbranch_scc1 .Lic1_c3
	s_mov_b32 s3, 0xd80
	s_mov_b32 s101, 0x14ff
	s_mov_b32 s52, 1
	s_branch .Lic1_go
.Lic1_c3:
	s_cmp_eq_u32 s0, 2
	s_cbranch_scc0 .Lic1_c4
	s_cmp_eq_u32 s1, 0
	s_cbranch_scc0 .Lic1_c4
	s_mov_b32 s3, 0x1500
	s_mov_b32 s101, 0x17bf
	s_mov_b32 s52, 1
	s_branch .Lic1_go

.Lic1_go:
	s_sub_i32 s0, s2, 150
	s_add_i32 s3, s3, s0
	s_sub_i32 s3, s3, 106
	v_writelane_b32 v255, s3, 0
	v_writelane_b32 v255, 1, 1
	s_movk_i32 s100, 106
	s_branch .Lconv_call

.Lconv_call:
	v_mov_b32_e32 v12, v136
	v_ashrrev_i32_e32 v11, 3, v12
	v_mov_b32_e32 v0, 0
	v_mov_b32_e32 v1, 0
	v_mov_b32_e32 v2, 0
	v_mov_b32_e32 v3, 0
	v_mov_b32_e32 v4, 0
	v_mov_b32_e32 v5, 0
	v_mov_b32_e32 v6, 0
	v_mov_b32_e32 v7, 0
	s_add_u32 s20, s94, 0x32a8900
	s_addc_u32 s21, s95, 0
	v_lshlrev_b32_e32 v8, 4, v136
	v_mov_b32_e32 v9, 0
	v_lshl_add_u64 v[8:9], v[8:9], 0, s[20:21]
	s_movk_i32 s83, 0x5ff
	v_readlane_b32 s44, v249, 45
	v_readlane_b32 s45, v249, 46
	s_branch .Lconv_pre

.LBB0_1658:
	s_cmp_lg_u32 s52, 2
	s_cselect_b64 s[0:1], -1, 0
	v_writelane_b32 v249, s0, 49
	s_cmp_lg_u32 s52, 0
	s_nop 0
	v_writelane_b32 v249, s1, 50
	s_cbranch_scc1 .LBB0_1765
	v_writelane_b32 v255, s2, 0
	v_writelane_b32 v255, 0, 1
	s_mov_b32 s100, s96
	s_movk_i32 s101, 0xfbf
	v_readlane_b32 s0, v252, 52
	v_readlane_b32 s1, v252, 53
	v_mov_b32_e32 v12, v136
	s_waitcnt vmcnt(0)
	v_mov_b32_e32 v3, 0
	v_cndmask_b32_e64 v0, 0, 1, s[0:1]
	v_cmp_ne_u32_e64 s[36:37], 1, v0
	v_ashrrev_i32_e32 v11, 3, v12
	s_andn2_b64 vcc, exec, s[0:1]
	v_mov_b32_e32 v2, v3
	v_mov_b32_e32 v1, v3
	v_mov_b32_e32 v0, v3
	v_mov_b32_e32 v7, v3
	v_mov_b32_e32 v6, v3
	v_mov_b32_e32 v5, v3
	v_mov_b32_e32 v4, v3
	s_cbranch_vccnz .LBB0_1711
	v_readlane_b32 s0, v252, 54
	v_readlane_b32 s1, v252, 55
	s_mov_b64 s[20:21], -1
	s_and_b64 vcc, exec, s[0:1]
	s_cbranch_vccz .LBB0_1670
	v_readlane_b32 s0, v252, 56
	v_readlane_b32 s1, v252, 57
	s_and_b64 vcc, exec, s[0:1]
	s_cbranch_vccz .LBB0_1685
	v_readlane_b32 s0, v252, 58
	v_readlane_b32 s1, v252, 59
	s_and_b64 vcc, exec, s[0:1]
	s_cbranch_vccz .LBB0_1682
	v_readlane_b32 s0, v252, 60
	v_readlane_b32 s1, v252, 61
	s_and_b64 vcc, exec, s[0:1]
	s_cbranch_vccz .LBB0_1679
	v_readlane_b32 s0, v252, 62
	v_readlane_b32 s1, v252, 63
	s_and_b64 vcc, exec, s[0:1]
	s_cbranch_vccz .LBB0_1676
	v_readlane_b32 s0, v250, 0
	v_readlane_b32 s1, v250, 1
	s_and_b64 vcc, exec, s[0:1]
	s_cbranch_vccz .LBB0_1673
	v_readlane_b32 s0, v250, 2
	v_readlane_b32 s1, v250, 3
	s_mov_b64 s[12:13], -1
	s_and_b64 vcc, exec, s[0:1]
	s_cbranch_vccz .LBB0_1668
	v_readlane_b32 s56, v251, 24
	s_mul_i32 s0, s52, 0xb00000
	v_readlane_b32 s66, v251, 34
	s_mul_hi_u32 s1, s52, 0xb00000
	v_readlane_b32 s67, v251, 35
	s_add_u32 s0, s66, s0
	v_readlane_b32 s57, v251, 25
	v_readlane_b32 s58, v251, 26
	v_readlane_b32 s59, v251, 27
	v_readlane_b32 s60, v251, 28
	v_readlane_b32 s61, v251, 29
	v_readlane_b32 s62, v251, 30
	v_readlane_b32 s63, v251, 31
	v_readlane_b32 s64, v251, 32
	v_readlane_b32 s65, v251, 33
	v_readlane_b32 s68, v251, 36
	v_readlane_b32 s69, v251, 37
	v_readlane_b32 s70, v251, 38
	v_readlane_b32 s71, v251, 39
	s_addc_u32 s1, s67, s1
	s_mov_b64 s[12:13], 0

.Lconv_pre:
	v_writelane_b32 v249, s44, 45
	s_mov_b32 s0, s52
	s_mov_b32 s1, s75
	v_writelane_b32 v249, s45, 46
	v_readlane_b32 s36, v251, 24
	s_mul_i32 s27, s52, 0xb00000
	s_lshl_b64 s[18:19], s[0:1], 22
	s_lshl_b64 s[20:21], s[0:1], 21
	v_readlane_b32 s46, v251, 34
	s_mul_hi_u32 s26, s52, 0xb00000
	v_readlane_b32 s47, v251, 35
	s_add_u32 s12, s46, s27
	s_mul_i32 s35, s52, 0x1600000
	s_movk_i32 s0, 0x90
	v_readlane_b32 s44, v251, 32
	s_addc_u32 s13, s47, s26
	s_mul_hi_u32 s34, s52, 0x1600000
	v_mul_lo_u32 v15, v11, s0
	v_readlane_b32 s45, v251, 33
	s_add_u32 s0, s44, s35
	v_readlane_b32 s38, v251, 26
	s_addc_u32 s1, s45, s34
	v_readlane_b32 s39, v251, 27
	s_add_u32 s18, s38, s18
	s_addc_u32 s19, s39, s19
	v_readlane_b32 s37, v251, 25
	s_add_u32 s36, s36, s20
	v_readlane_b32 s56, v251, 8
	s_addc_u32 s37, s37, s21
	v_readlane_b32 s70, v251, 22
	v_readlane_b32 s71, v251, 23
	s_add_u32 s38, s70, s20
	s_mul_i32 s55, s52, 0x1418000
	v_readlane_b32 s60, v251, 12
	s_addc_u32 s39, s71, s21
	s_mul_hi_u32 s54, s52, 0x1418000
	v_readlane_b32 s61, v251, 13
	s_add_u32 s44, s60, s55
	v_readlane_b32 s42, v251, 30
	s_addc_u32 s45, s61, s54
	v_readlane_b32 s43, v251, 31
	s_add_u32 s42, s42, s27
	v_lshlrev_b32_e32 v13, 3, v12
	v_lshrrev_b32_e32 v12, 3, v12
	v_readlane_b32 s40, v251, 28
	s_addc_u32 s43, s43, s26
	v_and_b32_e32 v10, 56, v13
	v_bitop3_b32 v16, v13, v11, 56 bitop3:0x6c
	v_bitop3_b32 v12, v13, 56, v12 bitop3:0x48
	v_readlane_b32 s41, v251, 29
	s_add_u32 s40, s40, s35
	v_mul_u32_u24_e32 v14, 0x90, v10
	s_addc_u32 s41, s41, s34
	s_mov_b32 s54, 0
	v_lshlrev_b32_e32 v16, 1, v16
	v_lshlrev_b32_e32 v17, 1, v12
	v_readlane_b32 s55, v255, 0
	v_mov_b64_e32 v[12:13], v[8:9]
	v_readlane_b32 s48, v251, 36
	v_readlane_b32 s49, v251, 37
	v_readlane_b32 s50, v251, 38
	v_readlane_b32 s51, v251, 39
	v_readlane_b32 s57, v251, 9
	v_readlane_b32 s58, v251, 10
	v_readlane_b32 s59, v251, 11
	v_readlane_b32 s62, v251, 14
	v_readlane_b32 s63, v251, 15
	v_readlane_b32 s64, v251, 16
	v_readlane_b32 s65, v251, 17
	v_readlane_b32 s66, v251, 18
	v_readlane_b32 s67, v251, 19
	v_readlane_b32 s68, v251, 20
	v_readlane_b32 s69, v251, 21
	s_branch .LBB0_1715

.LBB0_1715:
	s_mul_i32 s20, s54, 0x2400
	s_add_i32 s56, s20, 0
	s_add_i32 s55, s55, s100
	s_cmp_gt_i32 s55, s101
	s_cselect_b64 s[46:47], -1, 0
	s_waitcnt vmcnt(0)
	v_cvt_pk_bf16_f32 v18, v0, v1
	v_add3_u32 v22, s56, v14, v16
	s_and_b64 vcc, exec, s[46:47]
	v_cvt_pk_bf16_f32 v19, v2, v3
	v_cvt_pk_bf16_f32 v20, v4, v5
	v_cvt_pk_bf16_f32 v21, v6, v7
	ds_write_b16 v22, v18
	ds_write_b16_d16_hi v22, v18 offset:144
	ds_write_b16 v22, v19 offset:288
	ds_write_b16_d16_hi v22, v19 offset:432
	ds_write_b16 v22, v20 offset:576
	ds_write_b16_d16_hi v22, v20 offset:720
	ds_write_b16 v22, v21 offset:864
	ds_write_b16_d16_hi v22, v21 offset:1008
	s_waitcnt lgkmcnt(0)
	s_barrier
	s_cbranch_vccnz .LBB0_1714
	s_cmpk_lt_i32 s55, 0x580
	s_cbranch_scc1 .LBB0_1740
	s_cmpk_gt_u32 s55, 0x83f
	s_mov_b64 s[26:27], -1
	s_cbranch_scc0 .LBB0_1738
	s_cmpk_gt_u32 s55, 0xd7f
	s_cbranch_scc0 .LBB0_1735
	s_cmpk_gt_u32 s55, 0xdff
	s_cbranch_scc0 .LBB0_1732
	s_cmpk_gt_u32 s55, 0xe7f
	s_cbranch_scc0 .LBB0_1729
	s_cmpk_gt_u32 s55, 0xf7f
	s_cbranch_scc0 .LBB0_1726
	s_cmpk_gt_u32 s55, 0x14ff
	s_mov_b64 s[20:21], -1
	s_cbranch_scc0 .LBB0_1724
	s_add_i32 s58, s55, 0xffffeb00
	s_mov_b64 s[20:21], 0

.LBB0_1764:
	s_barrier
	v_readlane_b32 s100, v255, 1
	s_cmp_eq_u32 s100, 1
	s_cbranch_scc1 .Lconv_ret1
	s_cmp_eq_u32 s100, 2
	s_cbranch_scc1 .Ltramp_ret2

	.amdhsa_kernel _Z14fwd_megakernel4Args
		.amdhsa_group_segment_fixed_size 0
		.amdhsa_private_segment_fixed_size 0
		.amdhsa_kernarg_size 432
		.amdhsa_user_sgpr_count 2
		.amdhsa_user_sgpr_dispatch_ptr 0
		.amdhsa_user_sgpr_queue_ptr 0
		.amdhsa_user_sgpr_kernarg_segment_ptr 1
		.amdhsa_user_sgpr_dispatch_id 0
		.amdhsa_user_sgpr_kernarg_preload_length 0
		.amdhsa_user_sgpr_kernarg_preload_offset 0
		.amdhsa_user_sgpr_private_segment_size 0
		.amdhsa_uses_dynamic_stack 0
		.amdhsa_enable_private_segment 0
		.amdhsa_system_sgpr_workgroup_id_x 1
		.amdhsa_system_sgpr_workgroup_id_y 0
		.amdhsa_system_sgpr_workgroup_id_z 0
		.amdhsa_system_sgpr_workgroup_info 0
		.amdhsa_system_vgpr_workitem_id 2
		.amdhsa_next_free_vgpr 256
		.amdhsa_next_free_sgpr 102
		.amdhsa_accum_offset 256
		.amdhsa_reserve_vcc 1
		.amdhsa_float_round_mode_32 0
		.amdhsa_float_round_mode_16_64 0
		.amdhsa_float_denorm_mode_32 3
		.amdhsa_float_denorm_mode_16_64 3
		.amdhsa_dx10_clamp 1
		.amdhsa_ieee_mode 1
		.amdhsa_fp16_overflow 0
		.amdhsa_tg_split 0
		.amdhsa_exception_fp_ieee_invalid_op 0
		.amdhsa_exception_fp_denorm_src 0
		.amdhsa_exception_fp_ieee_div_zero 0
		.amdhsa_exception_fp_ieee_overflow 0
		.amdhsa_exception_fp_ieee_underflow 0
		.amdhsa_exception_fp_ieee_inexact 0
		.amdhsa_exception_int_div_zero 0
	.end_amdhsa_kernel

amdhsa.kernels:
  - .agpr_count:     0
    .args:
      - .offset:         0
        .size:           176
        .value_kind:     by_value
      - .offset:         176
        .size:           4
        .value_kind:     hidden_block_count_x
      - .offset:         180
        .size:           4
        .value_kind:     hidden_block_count_y
      - .offset:         184
        .size:           4
        .value_kind:     hidden_block_count_z
      - .offset:         188
        .size:           2
        .value_kind:     hidden_group_size_x
      - .offset:         190
        .size:           2
        .value_kind:     hidden_group_size_y
      - .offset:         192
        .size:           2
        .value_kind:     hidden_group_size_z
      - .offset:         194
        .size:           2
        .value_kind:     hidden_remainder_x
      - .offset:         196
        .size:           2
        .value_kind:     hidden_remainder_y
      - .offset:         198
        .size:           2
        .value_kind:     hidden_remainder_z
      - .offset:         216
        .size:           8
        .value_kind:     hidden_global_offset_x
      - .offset:         224
        .size:           8
        .value_kind:     hidden_global_offset_y
      - .offset:         232
        .size:           8
        .value_kind:     hidden_global_offset_z
      - .offset:         240
        .size:           2
        .value_kind:     hidden_grid_dims
      - .offset:         264
        .size:           8
        .value_kind:     hidden_multigrid_sync_arg
      - .offset:         296
        .size:           4
        .value_kind:     hidden_dynamic_lds_size
    .group_segment_fixed_size: 0
    .kernarg_segment_align: 8
    .kernarg_segment_size: 432
    .language:       OpenCL C
    .language_version:
      - 2
      - 0
    .max_flat_workgroup_size: 512
    .name:           _Z14fwd_megakernel4Args
    .private_segment_fixed_size: 0
    .sgpr_count:     108
    .sgpr_spill_count: 273
    .symbol:         _Z14fwd_megakernel4Args.kd
    .uniform_work_group_size: 1
    .uses_dynamic_stack: false
    .vgpr_count:     256
    .vgpr_spill_count: 0
    .wavefront_size: 64
